# v30 + strategy 6.4: attention loop segments lead with their resident-input MFMAs; the K/V prefetch address VALU and global loads moved behind that leading MFMA run (4 sites)
# speedup vs baseline: 1.0031x; 1.0031x over previous
.LBB0_513:
	v_mul_f32_e32 v216, 0xbdd53b94, v214
	v_fmamk_f32 v12, v98, 0x3dd53b94, v216
	s_sub_i32 s2, s36, 64
	v_fmamk_f32 v16, v102, 0x3dd53b94, v216
	v_fmamk_f32 v102, v108, 0x3dd53b94, v216
	v_exp_f32_e32 v108, v12
	v_add_u32_e32 v12, 0x12000, v204
	s_min_i32 s2, s2, s34
	v_fmamk_f32 v13, v99, 0x3dd53b94, v216
	s_waitcnt vmcnt(4)
	ds_write_b128 v203, v[146:149] offset:49152
	s_waitcnt vmcnt(3)
	ds_write_b128 v203, v[150:153] offset:57344
	s_waitcnt vmcnt(2)
	ds_write_b128 v12, v[154:157]
	v_or_b32_e32 v12, s2, v171
	v_fmamk_f32 v17, v103, 0x3dd53b94, v216
	v_fmamk_f32 v103, v109, 0x3dd53b94, v216
	v_fmamk_f32 v84, v84, 0x3dd53b94, v216
	v_exp_f32_e32 v109, v13
	v_ashrrev_i32_e32 v13, 31, v12
	v_fmamk_f32 v85, v85, 0x3dd53b94, v216
	v_exp_f32_e32 v221, v84
	v_lshlrev_b64 v[12:13], 13, v[12:13]
	v_add_u32_e32 v84, s2, v173
	v_fmamk_f32 v14, v100, 0x3dd53b94, v216
	v_fmamk_f32 v15, v101, 0x3dd53b94, v216
	v_fmamk_f32 v100, v106, 0x3dd53b94, v216
	v_fmamk_f32 v101, v107, 0x3dd53b94, v216
	v_fmamk_f32 v106, v112, 0x3dd53b94, v216
	v_fmamk_f32 v107, v113, 0x3dd53b94, v216
	v_exp_f32_e32 v112, v16
	v_exp_f32_e32 v113, v17
	v_exp_f32_e32 v222, v85
	v_lshl_add_u64 v[16:17], v[186:187], 0, v[12:13]
	v_add_u32_e32 v12, s2, v190
	v_ashrrev_i32_e32 v85, 31, v84
	v_ashrrev_i32_e32 v13, 31, v12
	v_lshlrev_b64 v[84:85], 7, v[84:85]
	v_fmamk_f32 v82, v82, 0x3dd53b94, v216
	v_fmamk_f32 v83, v83, 0x3dd53b94, v216
	s_waitcnt lgkmcnt(0)
	s_barrier
	v_lshlrev_b64 v[12:13], 13, v[12:13]
	v_lshl_add_u64 v[84:85], v[188:189], 0, v[84:85]
	v_fmamk_f32 v98, v104, 0x3dd53b94, v216
	v_fmamk_f32 v99, v105, 0x3dd53b94, v216
	v_fmamk_f32 v104, v110, 0x3dd53b94, v216
	v_fmamk_f32 v105, v111, 0x3dd53b94, v216
	v_exp_f32_e32 v110, v14
	v_exp_f32_e32 v111, v15
	v_exp_f32_e32 v219, v82
	v_exp_f32_e32 v220, v83
	v_lshl_add_u64 v[82:83], v[186:187], 0, v[12:13]
	global_load_dwordx4 v[12:15], v[16:17], off
	global_load_dwordx4 v[146:149], v[82:83], off
	global_load_dwordx4 v[150:153], v[84:85], off
	v_add_f32_e32 v84, 0, v108
	v_add_f32_e32 v84, v109, v84
	v_exp_f32_e32 v98, v98
	v_add_f32_e32 v84, v110, v84
	v_exp_f32_e32 v99, v99
	v_add_f32_e32 v84, v111, v84
	v_exp_f32_e32 v100, v100
	v_add_f32_e32 v84, v112, v84
	v_exp_f32_e32 v101, v101
	v_add_f32_e32 v84, v113, v84
	v_exp_f32_e32 v102, v102
	v_add_f32_e32 v84, v98, v84
	v_exp_f32_e32 v103, v103
	v_add_f32_e32 v84, v99, v84
	v_exp_f32_e32 v104, v104
	v_add_f32_e32 v84, v100, v84
	v_exp_f32_e32 v105, v105
	v_add_f32_e32 v84, v101, v84
	v_exp_f32_e32 v106, v106
	v_add_f32_e32 v84, v102, v84
	v_exp_f32_e32 v107, v107
	v_add_f32_e32 v84, v103, v84
	v_add_f32_e32 v84, v104, v84
	v_add_f32_e32 v84, v105, v84
	v_add_f32_e32 v84, v106, v84
	v_fmamk_f32 v86, v86, 0x3dd53b94, v216
	v_add_f32_e32 v84, v107, v84
	v_fmamk_f32 v87, v87, 0x3dd53b94, v216
	v_exp_f32_e32 v154, v86
	v_add_f32_e32 v84, v219, v84
	v_fmamk_f32 v88, v88, 0x3dd53b94, v216
	v_exp_f32_e32 v155, v87
	v_add_f32_e32 v84, v220, v84
	v_fmamk_f32 v89, v89, 0x3dd53b94, v216
	v_exp_f32_e32 v156, v88
	v_add_f32_e32 v84, v221, v84
	v_fmamk_f32 v90, v90, 0x3dd53b94, v216
	v_exp_f32_e32 v157, v89
	v_add_f32_e32 v84, v222, v84
	v_fmamk_f32 v91, v91, 0x3dd53b94, v216
	v_exp_f32_e32 v223, v90
	v_add_f32_e32 v84, v154, v84
	v_fmamk_f32 v92, v92, 0x3dd53b94, v216
	v_exp_f32_e32 v224, v91
	v_add_f32_e32 v84, v155, v84
	v_fmamk_f32 v93, v93, 0x3dd53b94, v216
	v_exp_f32_e32 v225, v92
	v_add_f32_e32 v84, v156, v84
	v_fmamk_f32 v94, v94, 0x3dd53b94, v216
	v_exp_f32_e32 v226, v93
	v_add_f32_e32 v84, v157, v84
	v_fmamk_f32 v95, v95, 0x3dd53b94, v216
	v_exp_f32_e32 v227, v94
	v_add_f32_e32 v84, v223, v84
	v_fmamk_f32 v96, v96, 0x3dd53b94, v216
	v_exp_f32_e32 v228, v95
	v_add_f32_e32 v84, v224, v84
	v_fmamk_f32 v97, v97, 0x3dd53b94, v216
	v_exp_f32_e32 v229, v96
	v_add_f32_e32 v84, v225, v84
	v_exp_f32_e32 v230, v97
	v_add_f32_e32 v84, v226, v84
	v_add_f32_e32 v84, v227, v84
	v_add_f32_e32 v84, v228, v84
	v_add_f32_e32 v84, v229, v84
	v_add_f32_e32 v217, v230, v84
	v_mov_b32_e32 v218, v217
	v_cvt_pk_bf16_f32 v84, v108, v109
	v_cvt_pk_bf16_f32 v85, v110, v111
	v_cvt_pk_bf16_f32 v86, v112, v113
	v_cvt_pk_bf16_f32 v87, v98, v99
	v_cvt_pk_bf16_f32 v88, v100, v101
	v_cvt_pk_bf16_f32 v89, v102, v103
	v_cvt_pk_bf16_f32 v90, v104, v105
	v_cvt_pk_bf16_f32 v91, v106, v107
	v_cvt_pk_bf16_f32 v92, v219, v220
	v_cvt_pk_bf16_f32 v93, v221, v222
	v_cvt_pk_bf16_f32 v94, v154, v155
	v_cvt_pk_bf16_f32 v95, v156, v157
	v_cvt_pk_bf16_f32 v96, v223, v224
	v_cvt_pk_bf16_f32 v97, v225, v226
	v_cvt_pk_bf16_f32 v98, v227, v228
	v_cvt_pk_bf16_f32 v99, v229, v230
	s_nop 1
	v_permlane32_swap_b32_e32 v217, v218
	v_permlane32_swap_b32_e32 v84, v86
	v_permlane32_swap_b32_e32 v85, v87
	v_permlane32_swap_b32_e32 v88, v90
	v_permlane32_swap_b32_e32 v89, v91
	v_permlane32_swap_b32_e32 v92, v94
	v_permlane32_swap_b32_e32 v93, v95
	v_permlane32_swap_b32_e32 v96, v98
	v_permlane32_swap_b32_e32 v97, v99
	ds_read_b64_tr_b16 v[100:101], v191 offset:0
	ds_read_b64_tr_b16 v[102:103], v191 offset:0x800
	ds_read_b64_tr_b16 v[104:105], v191 offset:0x1000
	ds_read_b64_tr_b16 v[106:107], v191 offset:0x1800
	ds_read_b64_tr_b16 v[108:109], v191 offset:0x2000
	ds_read_b64_tr_b16 v[110:111], v191 offset:0x2800
	ds_read_b64_tr_b16 v[154:155], v191 offset:0x3000
	ds_read_b64_tr_b16 v[156:157], v191 offset:0x3800
	s_waitcnt lgkmcnt(0)
	s_nop 0
	v_mfma_f32_32x32x16_bf16 v[66:81], v[84:87], v[100:103], v[66:81]
	ds_read_b64_tr_b16 v[100:101], v191 offset:0x200
	ds_read_b64_tr_b16 v[102:103], v191 offset:0xa00
	v_mfma_f32_32x32x16_bf16 v[66:81], v[88:91], v[104:107], v[66:81]
	ds_read_b64_tr_b16 v[104:105], v191 offset:0x1200
	ds_read_b64_tr_b16 v[106:107], v191 offset:0x1a00
	v_mfma_f32_32x32x16_bf16 v[66:81], v[92:95], v[108:111], v[66:81]
	ds_read_b64_tr_b16 v[108:109], v191 offset:0x2200
	ds_read_b64_tr_b16 v[110:111], v191 offset:0x2a00
	ds_read_b64_tr_b16 v[220:221], v191 offset:0x3200
	ds_read_b64_tr_b16 v[222:223], v191 offset:0x3a00
	s_waitcnt lgkmcnt(0)
	v_mfma_f32_32x32x16_bf16 v[66:81], v[96:99], v[154:157], v[66:81]
	v_mfma_f32_32x32x16_bf16 v[50:65], v[84:87], v[100:103], v[50:65]
	ds_read_b64_tr_b16 v[100:101], v191 offset:0x400
	ds_read_b64_tr_b16 v[102:103], v191 offset:0xc00
	v_mfma_f32_32x32x16_bf16 v[50:65], v[88:91], v[104:107], v[50:65]
	ds_read_b64_tr_b16 v[104:105], v191 offset:0x1400
	ds_read_b64_tr_b16 v[106:107], v191 offset:0x1c00
	v_mfma_f32_32x32x16_bf16 v[50:65], v[92:95], v[108:111], v[50:65]
	ds_read_b64_tr_b16 v[108:109], v191 offset:0x2400
	ds_read_b64_tr_b16 v[110:111], v191 offset:0x2c00
	ds_read_b64_tr_b16 v[154:155], v191 offset:0x3400
	ds_read_b64_tr_b16 v[156:157], v191 offset:0x3c00
	s_waitcnt lgkmcnt(0)
	v_mfma_f32_32x32x16_bf16 v[50:65], v[96:99], v[220:223], v[50:65]
	v_mfma_f32_32x32x16_bf16 v[34:49], v[84:87], v[100:103], v[34:49]
	ds_read_b64_tr_b16 v[100:101], v191 offset:0x600
	ds_read_b64_tr_b16 v[102:103], v191 offset:0xe00
	v_mfma_f32_32x32x16_bf16 v[34:49], v[88:91], v[104:107], v[34:49]
	ds_read_b64_tr_b16 v[104:105], v191 offset:0x1600
	ds_read_b64_tr_b16 v[106:107], v191 offset:0x1e00
	v_mfma_f32_32x32x16_bf16 v[34:49], v[92:95], v[108:111], v[34:49]
	ds_read_b64_tr_b16 v[108:109], v191 offset:0x2600
	ds_read_b64_tr_b16 v[110:111], v191 offset:0x2e00
	ds_read_b64_tr_b16 v[220:221], v191 offset:0x3600
	ds_read_b64_tr_b16 v[222:223], v191 offset:0x3e00
	s_waitcnt lgkmcnt(0)
	v_mfma_f32_32x32x16_bf16 v[34:49], v[96:99], v[154:157], v[34:49]
	s_waitcnt vmcnt(4)
	ds_write_b128 v205, v[4:7] offset:16384
	s_waitcnt vmcnt(3)
	ds_write_b128 v206, v[8:11] offset:16384
	s_waitcnt lgkmcnt(0)
	s_barrier
	v_mfma_f32_32x32x16_bf16 v[18:33], v[84:87], v[100:103], v[18:33]
	v_mfma_f32_32x32x16_bf16 v[18:33], v[88:91], v[104:107], v[18:33]
	v_mfma_f32_32x32x16_bf16 v[18:33], v[92:95], v[108:111], v[18:33]
	v_mfma_f32_32x32x16_bf16 v[18:33], v[96:99], v[220:223], v[18:33]
	global_load_dwordx4 v[8:11], v[16:17], off offset:256
	global_load_dwordx4 v[4:7], v[82:83], off offset:256
	ds_read_b128 v[82:85], v207 offset:49152
	ds_read_b128 v[86:89], v207 offset:57344
	ds_read_b128 v[154:157], v208 offset:49152
	ds_read_b128 v[220:223], v208 offset:57344
	ds_read_b128 v[224:227], v209 offset:49152
	ds_read_b128 v[228:231], v209 offset:57344
	ds_read_b128 v[232:235], v210 offset:49152
	ds_read_b128 v[236:239], v210 offset:57344
	s_waitcnt lgkmcnt(7)
	v_mfma_f32_32x32x16_bf16 v[98:113], v[82:85], v[114:117], 0
	s_waitcnt lgkmcnt(6)
	v_mfma_f32_32x32x16_bf16 v[82:97], v[86:89], v[114:117], 0
	s_waitcnt lgkmcnt(5)
	v_mfma_f32_32x32x16_bf16 v[98:113], v[154:157], v[118:121], v[98:113]
	s_waitcnt lgkmcnt(4)
	v_mfma_f32_32x32x16_bf16 v[82:97], v[220:223], v[118:121], v[82:97]
	ds_read_b128 v[154:157], v207 offset:49280
	ds_read_b128 v[220:223], v207 offset:57472
	ds_read_b128 v[240:243], v208 offset:49280
	ds_read_b128 v[244:247], v208 offset:57472
	s_waitcnt lgkmcnt(7)
	v_mfma_f32_32x32x16_bf16 v[98:113], v[224:227], v[122:125], v[98:113]
	s_waitcnt lgkmcnt(6)
	v_mfma_f32_32x32x16_bf16 v[82:97], v[228:231], v[122:125], v[82:97]
	s_waitcnt lgkmcnt(5)
	v_mfma_f32_32x32x16_bf16 v[98:113], v[232:235], v[126:129], v[98:113]
	s_waitcnt lgkmcnt(4)
	v_mfma_f32_32x32x16_bf16 v[82:97], v[236:239], v[126:129], v[82:97]
	ds_read_b128 v[224:227], v209 offset:49280
	ds_read_b128 v[228:231], v209 offset:57472
	ds_read_b128 v[232:235], v210 offset:49280
	ds_read_b128 v[236:239], v210 offset:57472
	s_waitcnt lgkmcnt(7)
	v_mfma_f32_32x32x16_bf16 v[98:113], v[154:157], v[130:133], v[98:113]
	s_waitcnt lgkmcnt(6)
	v_mfma_f32_32x32x16_bf16 v[82:97], v[220:223], v[130:133], v[82:97]
	s_waitcnt lgkmcnt(5)
	v_mfma_f32_32x32x16_bf16 v[98:113], v[240:243], v[134:137], v[98:113]
	s_waitcnt lgkmcnt(4)
	v_mfma_f32_32x32x16_bf16 v[82:97], v[244:247], v[134:137], v[82:97]
	v_add_u32_e32 v16, v199, v194
	ds_read_b128 v[154:157], v16 offset:4096
	ds_read_b128 v[220:223], v16
	ds_read_b128 v[240:243], v212
	s_waitcnt lgkmcnt(6)
	v_mfma_f32_32x32x16_bf16 v[98:113], v[224:227], v[138:141], v[98:113]
	s_waitcnt lgkmcnt(5)
	v_mfma_f32_32x32x16_bf16 v[82:97], v[228:231], v[138:141], v[82:97]
	s_waitcnt lgkmcnt(4)
	v_mfma_f32_32x32x16_bf16 v[98:113], v[232:235], v[142:145], v[98:113]
	s_waitcnt lgkmcnt(3)
	v_mfma_f32_32x32x16_bf16 v[82:97], v[236:239], v[142:145], v[82:97]
	v_add_u32_e32 v16, v199, v195
	ds_read_b128 v[224:227], v16 offset:4096
	ds_read_b128 v[228:231], v16
	ds_read_b128 v[232:235], v212 offset:1024
	s_waitcnt lgkmcnt(3)
	v_mfma_f32_32x32x16_bf16 v[98:113], v[220:223], v[240:243], v[98:113]
	v_mfma_f32_32x32x16_bf16 v[82:97], v[154:157], v[240:243], v[82:97]
	v_add_u32_e32 v16, v199, v196
	ds_read_b128 v[154:157], v16 offset:4096
	ds_read_b128 v[220:223], v16
	ds_read_b128 v[236:239], v212 offset:2048
	s_waitcnt lgkmcnt(3)
	v_mfma_f32_32x32x16_bf16 v[98:113], v[228:231], v[232:235], v[98:113]
	v_mfma_f32_32x32x16_bf16 v[82:97], v[224:227], v[232:235], v[82:97]
	v_add_u32_e32 v16, v199, v197
	ds_read_b128 v[224:227], v16 offset:4096
	ds_read_b128 v[228:231], v16
	ds_read_b128 v[232:235], v212 offset:3072
	s_waitcnt lgkmcnt(3)
	v_mfma_f32_32x32x16_bf16 v[98:113], v[220:223], v[236:239], v[98:113]
	v_mfma_f32_32x32x16_bf16 v[82:97], v[154:157], v[236:239], v[82:97]
	s_waitcnt lgkmcnt(0)
	v_mfma_f32_32x32x16_bf16 v[98:113], v[228:231], v[232:235], v[98:113]
	s_add_i32 s2, s36, 0xffffffbf
	s_cmp_le_u32 s2, s31
	v_mfma_f32_32x32x16_bf16 v[82:97], v[224:227], v[232:235], v[82:97]
	s_cbranch_scc1 .LBB0_515
	v_subrev_u32_e32 v16, 64, v215
	v_cmp_gt_u32_e32 vcc, s27, v16
	v_add_u32_e32 v17, 0xffffffa0, v215
	s_nop 4
	v_cndmask_b32_e32 v98, v211, v98, vcc
	v_cmp_gt_u32_e32 vcc, s27, v17
	s_nop 1
	v_cndmask_b32_e32 v82, v211, v82, vcc
	v_cmp_lt_i32_e32 vcc, 0, v16
	v_add_u32_e32 v16, 0xffffff9f, v215
	s_nop 0
	v_cndmask_b32_e32 v99, v211, v99, vcc
	v_cmp_gt_u32_e32 vcc, s27, v16
	v_add_u32_e32 v16, 0xffffffbe, v215
	s_nop 0
	v_cndmask_b32_e32 v83, v211, v83, vcc
	v_cmp_gt_u32_e32 vcc, s27, v16
	v_add_u32_e32 v16, 0xffffff9e, v215
	s_nop 0
	v_cndmask_b32_e32 v100, v211, v100, vcc
	v_cmp_gt_u32_e32 vcc, s27, v16
	v_add_u32_e32 v16, 0xffffffbd, v215
	s_nop 0
	v_cndmask_b32_e32 v84, v211, v84, vcc
	v_cmp_gt_u32_e32 vcc, s27, v16
	v_add_u32_e32 v16, 0xffffff9d, v215
	s_nop 0
	v_cndmask_b32_e32 v101, v211, v101, vcc
	v_cmp_gt_u32_e32 vcc, s27, v16
	v_add_u32_e32 v16, 0xffffffb8, v215
	s_nop 0
	v_cndmask_b32_e32 v85, v211, v85, vcc
	v_cmp_gt_u32_e32 vcc, s27, v16
	v_add_u32_e32 v16, 0xffffff98, v215
	s_nop 0
	v_cndmask_b32_e32 v102, v211, v102, vcc
	v_cmp_gt_u32_e32 vcc, s27, v16
	v_add_u32_e32 v16, 0xffffffb7, v215
	s_nop 0
	v_cndmask_b32_e32 v86, v211, v86, vcc
	v_cmp_gt_u32_e32 vcc, s27, v16
	v_add_u32_e32 v16, 0xffffff97, v215
	s_nop 0
	v_cndmask_b32_e32 v103, v211, v103, vcc
	v_cmp_gt_u32_e32 vcc, s27, v16
	v_add_u32_e32 v16, 0xffffffb6, v215
	s_nop 0
	v_cndmask_b32_e32 v87, v211, v87, vcc
	v_cmp_gt_u32_e32 vcc, s27, v16
	v_add_u32_e32 v16, 0xffffff96, v215
	s_nop 0
	v_cndmask_b32_e32 v104, v211, v104, vcc
	v_cmp_gt_u32_e32 vcc, s27, v16
	v_add_u32_e32 v16, 0xffffffb5, v215
	s_nop 0
	v_cndmask_b32_e32 v88, v211, v88, vcc
	v_cmp_gt_u32_e32 vcc, s27, v16
	v_add_u32_e32 v16, 0xffffff95, v215
	s_nop 0
	v_cndmask_b32_e32 v105, v211, v105, vcc
	v_cmp_gt_u32_e32 vcc, s27, v16
	v_add_u32_e32 v16, 0xffffffb0, v215
	s_nop 0
	v_cndmask_b32_e32 v89, v211, v89, vcc
	v_cmp_gt_u32_e32 vcc, s27, v16
	v_add_u32_e32 v16, 0xffffff90, v215
	s_nop 0
	v_cndmask_b32_e32 v106, v211, v106, vcc
	v_cmp_gt_u32_e32 vcc, s27, v16
	v_add_u32_e32 v16, 0xffffffaf, v215
	s_nop 0
	v_cndmask_b32_e32 v90, v211, v90, vcc
	v_cmp_gt_u32_e32 vcc, s27, v16
	v_add_u32_e32 v16, 0xffffff8f, v215
	s_nop 0
	v_cndmask_b32_e32 v107, v211, v107, vcc
	v_cmp_gt_u32_e32 vcc, s27, v16
	v_add_u32_e32 v16, 0xffffffae, v215
	s_nop 0
	v_cndmask_b32_e32 v91, v211, v91, vcc
	v_cmp_gt_u32_e32 vcc, s27, v16
	v_add_u32_e32 v16, 0xffffff8e, v215
	s_nop 0
	v_cndmask_b32_e32 v108, v211, v108, vcc
	v_cmp_gt_u32_e32 vcc, s27, v16
	v_add_u32_e32 v16, 0xffffffad, v215
	s_nop 0
	v_cndmask_b32_e32 v92, v211, v92, vcc
	v_cmp_gt_u32_e32 vcc, s27, v16
	v_add_u32_e32 v16, 0xffffff8d, v215
	s_nop 0
	v_cndmask_b32_e32 v109, v211, v109, vcc
	v_cmp_gt_u32_e32 vcc, s27, v16
	v_add_u32_e32 v16, 0xffffffa8, v215
	s_nop 0
	v_cndmask_b32_e32 v93, v211, v93, vcc
	v_cmp_gt_u32_e32 vcc, s27, v16
	v_add_u32_e32 v16, 0xffffff88, v215
	s_nop 0
	v_cndmask_b32_e32 v110, v211, v110, vcc
	v_cmp_gt_u32_e32 vcc, s27, v16
	v_add_u32_e32 v16, 0xffffffa7, v215
	s_nop 0
	v_cndmask_b32_e32 v94, v211, v94, vcc
	v_cmp_gt_u32_e32 vcc, s27, v16
	v_add_u32_e32 v16, 0xffffff87, v215
	s_nop 0
	v_cndmask_b32_e32 v111, v211, v111, vcc
	v_cmp_gt_u32_e32 vcc, s27, v16
	v_add_u32_e32 v16, 0xffffffa6, v215
	s_nop 0
	v_cndmask_b32_e32 v95, v211, v95, vcc
	v_cmp_gt_u32_e32 vcc, s27, v16
	v_add_u32_e32 v16, 0xffffff86, v215
	s_nop 0
	v_cndmask_b32_e32 v112, v211, v112, vcc
	v_cmp_gt_u32_e32 vcc, s27, v16
	v_add_u32_e32 v16, 0xffffffa5, v215
	s_nop 0
	v_cndmask_b32_e32 v96, v211, v96, vcc
	v_cmp_gt_u32_e32 vcc, s27, v16
	v_add_u32_e32 v16, 0xffffff85, v215
	s_nop 0
	v_cndmask_b32_e32 v113, v211, v113, vcc
	v_cmp_gt_u32_e32 vcc, s27, v16
	s_nop 1
	v_cndmask_b32_e32 v97, v211, v97, vcc

.LBB0_1494:
	s_add_i32 s2, s83, 2
	v_mul_f32_e32 v199, 0xbe0293ee, v161
	s_lshl_b32 s33, s2, 6
	v_fmamk_f32 v2, v98, 0x3e0293ee, v199
	s_min_i32 s8, s33, s78
	v_fmamk_f32 v13, v100, 0x3e0293ee, v199
	v_fmamk_f32 v100, v107, 0x3e0293ee, v199
	v_exp_f32_e32 v107, v2
	v_or_b32_e32 v2, s8, v178
	v_fmamk_f32 v12, v99, 0x3e0293ee, v199
	v_fmamk_f32 v16, v103, 0x3e0293ee, v199
	v_fmamk_f32 v17, v104, 0x3e0293ee, v199
	s_waitcnt vmcnt(3)
	ds_write_b128 v188, v[146:149] offset:49152
	s_waitcnt vmcnt(2)
	ds_write_b128 v188, v[150:153] offset:57344
	v_lshlrev_b32_e32 v2, 11, v2
	v_fmamk_f32 v14, v101, 0x3e0293ee, v199
	v_fmamk_f32 v15, v102, 0x3e0293ee, v199
	v_fmamk_f32 v98, v105, 0x3e0293ee, v199
	v_fmamk_f32 v99, v106, 0x3e0293ee, v199
	v_fmamk_f32 v101, v108, 0x3e0293ee, v199
	v_fmamk_f32 v102, v109, 0x3e0293ee, v199
	v_fmamk_f32 v105, v112, 0x3e0293ee, v199
	v_fmamk_f32 v106, v113, 0x3e0293ee, v199
	v_fmamk_f32 v82, v82, 0x3e0293ee, v199
	v_fmamk_f32 v83, v83, 0x3e0293ee, v199
	v_exp_f32_e32 v108, v12
	v_exp_f32_e32 v109, v13
	v_exp_f32_e32 v112, v16
	v_exp_f32_e32 v113, v17
	s_waitcnt lgkmcnt(0)
	s_barrier
	v_lshl_add_u64 v[12:13], v[170:171], 0, v[2:3]
	v_add_lshl_u32 v16, s8, v179, 11
	v_mov_b32_e32 v17, v3
	v_fmamk_f32 v103, v110, 0x3e0293ee, v199
	v_fmamk_f32 v104, v111, 0x3e0293ee, v199
	v_exp_f32_e32 v110, v14
	v_exp_f32_e32 v111, v15
	v_exp_f32_e32 v206, v82
	v_exp_f32_e32 v207, v83
	v_lshl_add_u64 v[82:83], v[170:171], 0, v[16:17]
	global_load_dwordx4 v[12:15], v[12:13], off
	s_nop 0
	global_load_dwordx4 v[146:149], v[82:83], off
	v_add_f32_e32 v82, 0, v107
	v_add_f32_e32 v82, v108, v82
	v_add_f32_e32 v82, v109, v82
	v_exp_f32_e32 v98, v98
	v_add_f32_e32 v82, v110, v82
	v_exp_f32_e32 v99, v99
	v_add_f32_e32 v82, v111, v82
	v_exp_f32_e32 v100, v100
	v_add_f32_e32 v82, v112, v82
	v_exp_f32_e32 v101, v101
	v_add_f32_e32 v82, v113, v82
	v_exp_f32_e32 v102, v102
	v_add_f32_e32 v82, v98, v82
	v_exp_f32_e32 v103, v103
	v_add_f32_e32 v82, v99, v82
	v_exp_f32_e32 v104, v104
	v_add_f32_e32 v82, v100, v82
	v_exp_f32_e32 v105, v105
	v_add_f32_e32 v82, v101, v82
	v_exp_f32_e32 v106, v106
	v_add_f32_e32 v82, v102, v82
	v_add_f32_e32 v82, v103, v82
	v_fmamk_f32 v84, v84, 0x3e0293ee, v199
	v_add_f32_e32 v82, v104, v82
	v_fmamk_f32 v85, v85, 0x3e0293ee, v199
	v_exp_f32_e32 v208, v84
	v_add_f32_e32 v82, v105, v82
	v_fmamk_f32 v86, v86, 0x3e0293ee, v199
	v_exp_f32_e32 v209, v85
	v_add_f32_e32 v82, v106, v82
	v_fmamk_f32 v87, v87, 0x3e0293ee, v199
	v_exp_f32_e32 v150, v86
	v_add_f32_e32 v82, v206, v82
	v_fmamk_f32 v88, v88, 0x3e0293ee, v199
	v_exp_f32_e32 v151, v87
	v_add_f32_e32 v82, v207, v82
	v_fmamk_f32 v89, v89, 0x3e0293ee, v199
	v_exp_f32_e32 v152, v88
	v_add_f32_e32 v82, v208, v82
	v_fmamk_f32 v90, v90, 0x3e0293ee, v199
	v_exp_f32_e32 v153, v89
	v_add_f32_e32 v82, v209, v82
	v_fmamk_f32 v91, v91, 0x3e0293ee, v199
	v_exp_f32_e32 v210, v90
	v_add_f32_e32 v82, v150, v82
	v_fmamk_f32 v92, v92, 0x3e0293ee, v199
	v_exp_f32_e32 v211, v91
	v_add_f32_e32 v82, v151, v82
	v_fmamk_f32 v93, v93, 0x3e0293ee, v199
	v_exp_f32_e32 v212, v92
	v_add_f32_e32 v82, v152, v82
	v_fmamk_f32 v94, v94, 0x3e0293ee, v199
	v_exp_f32_e32 v213, v93
	v_add_f32_e32 v82, v153, v82
	v_fmamk_f32 v95, v95, 0x3e0293ee, v199
	v_exp_f32_e32 v214, v94
	v_add_f32_e32 v82, v210, v82
	v_fmamk_f32 v96, v96, 0x3e0293ee, v199
	v_exp_f32_e32 v215, v95
	v_add_f32_e32 v82, v211, v82
	v_fmamk_f32 v97, v97, 0x3e0293ee, v199
	v_exp_f32_e32 v216, v96
	v_add_f32_e32 v82, v212, v82
	v_exp_f32_e32 v97, v97
	v_add_f32_e32 v82, v213, v82
	v_add_f32_e32 v82, v214, v82
	v_add_f32_e32 v82, v215, v82
	v_add_f32_e32 v82, v216, v82
	v_add_f32_e32 v204, v97, v82
	v_mov_b32_e32 v205, v204
	v_cvt_pk_bf16_f32 v82, v107, v108
	v_cvt_pk_bf16_f32 v83, v109, v110
	v_cvt_pk_bf16_f32 v84, v111, v112
	v_cvt_pk_bf16_f32 v85, v113, v98
	v_cvt_pk_bf16_f32 v86, v99, v100
	v_cvt_pk_bf16_f32 v87, v101, v102
	v_cvt_pk_bf16_f32 v88, v103, v104
	v_cvt_pk_bf16_f32 v89, v105, v106
	v_cvt_pk_bf16_f32 v90, v206, v207
	v_cvt_pk_bf16_f32 v91, v208, v209
	v_cvt_pk_bf16_f32 v92, v150, v151
	v_cvt_pk_bf16_f32 v93, v152, v153
	v_cvt_pk_bf16_f32 v94, v210, v211
	v_cvt_pk_bf16_f32 v95, v212, v213
	v_cvt_pk_bf16_f32 v96, v214, v215
	v_cvt_pk_bf16_f32 v97, v216, v97
	s_nop 1
	v_permlane32_swap_b32_e32 v204, v205
	v_permlane32_swap_b32_e32 v82, v84
	v_permlane32_swap_b32_e32 v83, v85
	v_permlane32_swap_b32_e32 v86, v88
	v_permlane32_swap_b32_e32 v87, v89
	v_permlane32_swap_b32_e32 v90, v92
	v_permlane32_swap_b32_e32 v91, v93
	v_permlane32_swap_b32_e32 v94, v96
	v_permlane32_swap_b32_e32 v95, v97
	ds_read_b64_tr_b16 v[98:99], v180 offset:0
	ds_read_b64_tr_b16 v[100:101], v180 offset:0x800
	ds_read_b64_tr_b16 v[102:103], v180 offset:0x1000
	ds_read_b64_tr_b16 v[104:105], v180 offset:0x1800
	ds_read_b64_tr_b16 v[106:107], v180 offset:0x2000
	ds_read_b64_tr_b16 v[108:109], v180 offset:0x2800
	ds_read_b64_tr_b16 v[110:111], v180 offset:0x3000
	ds_read_b64_tr_b16 v[112:113], v180 offset:0x3800
	s_waitcnt lgkmcnt(0)
	s_nop 0
	v_mfma_f32_32x32x16_bf16 v[66:81], v[82:85], v[98:101], v[66:81]
	ds_read_b64_tr_b16 v[98:99], v180 offset:0x200
	ds_read_b64_tr_b16 v[100:101], v180 offset:0xa00
	v_mfma_f32_32x32x16_bf16 v[66:81], v[86:89], v[102:105], v[66:81]
	ds_read_b64_tr_b16 v[102:103], v180 offset:0x1200
	ds_read_b64_tr_b16 v[104:105], v180 offset:0x1a00
	v_mfma_f32_32x32x16_bf16 v[66:81], v[90:93], v[106:109], v[66:81]
	ds_read_b64_tr_b16 v[106:107], v180 offset:0x2200
	ds_read_b64_tr_b16 v[108:109], v180 offset:0x2a00
	ds_read_b64_tr_b16 v[150:151], v180 offset:0x3200
	ds_read_b64_tr_b16 v[152:153], v180 offset:0x3a00
	s_waitcnt lgkmcnt(0)
	v_mfma_f32_32x32x16_bf16 v[66:81], v[94:97], v[110:113], v[66:81]
	v_mfma_f32_32x32x16_bf16 v[50:65], v[82:85], v[98:101], v[50:65]
	ds_read_b64_tr_b16 v[98:99], v180 offset:0x400
	ds_read_b64_tr_b16 v[100:101], v180 offset:0xc00
	v_mfma_f32_32x32x16_bf16 v[50:65], v[86:89], v[102:105], v[50:65]
	ds_read_b64_tr_b16 v[102:103], v180 offset:0x1400
	ds_read_b64_tr_b16 v[104:105], v180 offset:0x1c00
	v_mfma_f32_32x32x16_bf16 v[50:65], v[90:93], v[106:109], v[50:65]
	ds_read_b64_tr_b16 v[106:107], v180 offset:0x2400
	ds_read_b64_tr_b16 v[108:109], v180 offset:0x2c00
	ds_read_b64_tr_b16 v[110:111], v180 offset:0x3400
	ds_read_b64_tr_b16 v[112:113], v180 offset:0x3c00
	s_waitcnt lgkmcnt(0)
	v_mfma_f32_32x32x16_bf16 v[50:65], v[94:97], v[150:153], v[50:65]
	v_mfma_f32_32x32x16_bf16 v[34:49], v[82:85], v[98:101], v[34:49]
	ds_read_b64_tr_b16 v[98:99], v180 offset:0x600
	ds_read_b64_tr_b16 v[100:101], v180 offset:0xe00
	v_mfma_f32_32x32x16_bf16 v[34:49], v[86:89], v[102:105], v[34:49]
	ds_read_b64_tr_b16 v[102:103], v180 offset:0x1600
	ds_read_b64_tr_b16 v[104:105], v180 offset:0x1e00
	v_mfma_f32_32x32x16_bf16 v[34:49], v[90:93], v[106:109], v[34:49]
	ds_read_b64_tr_b16 v[106:107], v180 offset:0x2600
	ds_read_b64_tr_b16 v[108:109], v180 offset:0x2e00
	ds_read_b64_tr_b16 v[150:151], v180 offset:0x3600
	ds_read_b64_tr_b16 v[152:153], v180 offset:0x3e00
	s_waitcnt lgkmcnt(0)
	v_mfma_f32_32x32x16_bf16 v[34:49], v[94:97], v[110:113], v[34:49]
	s_waitcnt vmcnt(3)
	ds_write_b128 v189, v[8:11] offset:16384
	s_waitcnt vmcnt(2)
	ds_write_b128 v190, v[4:7] offset:16384
	s_waitcnt lgkmcnt(0)
	s_barrier
	v_mfma_f32_32x32x16_bf16 v[18:33], v[82:85], v[98:101], v[18:33]
	v_mfma_f32_32x32x16_bf16 v[18:33], v[86:89], v[102:105], v[18:33]
	v_mfma_f32_32x32x16_bf16 v[18:33], v[90:93], v[106:109], v[18:33]
	v_mfma_f32_32x32x16_bf16 v[18:33], v[94:97], v[150:153], v[18:33]
	v_lshl_add_u64 v[4:5], v[168:169], 0, v[2:3]
	v_lshl_add_u64 v[8:9], v[168:169], 0, v[16:17]
	global_load_dwordx4 v[4:7], v[4:5], off
	s_nop 0
	global_load_dwordx4 v[8:11], v[8:9], off
	ds_read_b128 v[82:85], v202 offset:49152
	ds_read_b128 v[86:89], v202 offset:57344
	ds_read_b128 v[150:153], v203 offset:49152
	ds_read_b128 v[206:209], v203 offset:57344
	ds_read_b128 v[210:213], v200 offset:49152
	ds_read_b128 v[214:217], v200 offset:57344
	ds_read_b128 v[218:221], v201 offset:49152
	ds_read_b128 v[222:225], v201 offset:57344
	s_waitcnt lgkmcnt(7)
	v_mfma_f32_32x32x16_bf16 v[98:113], v[82:85], v[114:117], 0
	s_waitcnt lgkmcnt(6)
	v_mfma_f32_32x32x16_bf16 v[82:97], v[86:89], v[114:117], 0
	s_waitcnt lgkmcnt(5)
	v_mfma_f32_32x32x16_bf16 v[98:113], v[150:153], v[118:121], v[98:113]
	s_waitcnt lgkmcnt(4)
	v_mfma_f32_32x32x16_bf16 v[82:97], v[206:209], v[118:121], v[82:97]
	ds_read_b128 v[150:153], v202 offset:49280
	ds_read_b128 v[206:209], v202 offset:57472
	ds_read_b128 v[226:229], v203 offset:49280
	ds_read_b128 v[230:233], v203 offset:57472
	s_waitcnt lgkmcnt(7)
	v_mfma_f32_32x32x16_bf16 v[98:113], v[210:213], v[122:125], v[98:113]
	s_waitcnt lgkmcnt(6)
	v_mfma_f32_32x32x16_bf16 v[82:97], v[214:217], v[122:125], v[82:97]
	s_waitcnt lgkmcnt(5)
	v_mfma_f32_32x32x16_bf16 v[98:113], v[218:221], v[126:129], v[98:113]
	s_waitcnt lgkmcnt(4)
	v_mfma_f32_32x32x16_bf16 v[82:97], v[222:225], v[126:129], v[82:97]
	ds_read_b128 v[210:213], v200 offset:49280
	ds_read_b128 v[214:217], v200 offset:57472
	ds_read_b128 v[218:221], v201 offset:49280
	ds_read_b128 v[200:203], v201 offset:57472
	s_waitcnt lgkmcnt(7)
	v_mfma_f32_32x32x16_bf16 v[98:113], v[150:153], v[130:133], v[98:113]
	s_waitcnt lgkmcnt(6)
	v_mfma_f32_32x32x16_bf16 v[82:97], v[206:209], v[130:133], v[82:97]
	s_waitcnt lgkmcnt(5)
	v_mfma_f32_32x32x16_bf16 v[98:113], v[226:229], v[134:137], v[98:113]
	s_waitcnt lgkmcnt(4)
	v_mfma_f32_32x32x16_bf16 v[82:97], v[230:233], v[134:137], v[82:97]
	s_waitcnt lgkmcnt(3)
	v_mfma_f32_32x32x16_bf16 v[98:113], v[210:213], v[138:141], v[98:113]
	s_or_b32 s8, s87, 0x7f
	s_cmp_le_i32 s8, s5
	s_waitcnt lgkmcnt(2)
	v_mfma_f32_32x32x16_bf16 v[82:97], v[214:217], v[138:141], v[82:97]
	s_waitcnt lgkmcnt(1)
	v_mfma_f32_32x32x16_bf16 v[98:113], v[218:221], v[142:145], v[98:113]
	s_waitcnt lgkmcnt(0)
	v_mfma_f32_32x32x16_bf16 v[82:97], v[200:203], v[142:145], v[82:97]
	s_cbranch_scc1 .LBB0_1496
	v_subrev_u32_e32 v2, s86, v187
	v_add_u32_e32 v2, v2, v195
	v_cmp_lt_i32_e64 s[66:67], 25, v2
	v_cmp_lt_i32_e64 s[68:69], 26, v2
	v_cmp_lt_i32_e64 s[64:65], 24, v2
	s_or_b64 s[66:67], s[68:69], s[66:67]
	v_cmp_lt_i32_e64 s[62:63], 23, v2
	s_or_b64 s[64:65], s[66:67], s[64:65]
	v_cmp_lt_i32_e64 s[60:61], 18, v2
	s_or_b64 s[62:63], s[64:65], s[62:63]
	v_cmp_lt_i32_e64 s[58:59], 17, v2
	s_or_b64 s[60:61], s[62:63], s[60:61]
	v_cmp_lt_i32_e64 s[56:57], 16, v2
	s_or_b64 s[58:59], s[60:61], s[58:59]
	v_cmp_lt_i32_e64 s[54:55], 15, v2
	s_or_b64 s[56:57], s[58:59], s[56:57]
	v_cmp_lt_i32_e64 s[52:53], 10, v2
	s_or_b64 s[54:55], s[56:57], s[54:55]
	v_cmp_lt_i32_e64 s[50:51], 9, v2
	s_or_b64 s[52:53], s[54:55], s[52:53]
	v_cmp_lt_i32_e64 s[48:49], 8, v2
	s_or_b64 s[50:51], s[52:53], s[50:51]
	v_cmp_lt_i32_e64 s[46:47], 7, v2
	s_or_b64 s[48:49], s[50:51], s[48:49]
	v_cmp_lt_i32_e64 s[44:45], 2, v2
	s_or_b64 s[46:47], s[48:49], s[46:47]
	v_cmp_lt_i32_e64 s[42:43], 1, v2
	s_or_b64 s[44:45], s[46:47], s[44:45]
	v_cmp_lt_i32_e64 s[40:41], 0, v2
	s_or_b64 s[42:43], s[44:45], s[42:43]
	v_cmp_lt_i32_e64 s[38:39], -1, v2
	s_or_b64 s[40:41], s[42:43], s[40:41]
	s_or_b64 s[38:39], s[40:41], s[38:39]
	v_cmp_lt_i32_e64 s[36:37], 57, v2
	v_cndmask_b32_e64 v98, v191, v98, s[38:39]
	v_cmp_lt_i32_e64 s[38:39], 58, v2
	v_cmp_lt_i32_e64 s[34:35], 56, v2
	s_or_b64 s[36:37], s[38:39], s[36:37]
	v_cmp_lt_i32_e64 s[30:31], 55, v2
	s_or_b64 s[34:35], s[36:37], s[34:35]
	v_cmp_lt_i32_e64 s[28:29], 50, v2
	s_or_b64 s[30:31], s[34:35], s[30:31]
	v_cmp_lt_i32_e64 s[26:27], 49, v2
	s_or_b64 s[28:29], s[30:31], s[28:29]
	v_cmp_lt_i32_e64 s[24:25], 48, v2
	s_or_b64 s[26:27], s[28:29], s[26:27]
	v_cmp_lt_i32_e64 s[22:23], 47, v2
	s_or_b64 s[24:25], s[26:27], s[24:25]
	v_cmp_lt_i32_e64 s[20:21], 42, v2
	s_or_b64 s[22:23], s[24:25], s[22:23]
	v_cmp_lt_i32_e64 s[18:19], 41, v2
	s_or_b64 s[20:21], s[22:23], s[20:21]
	v_cmp_lt_i32_e64 s[16:17], 40, v2
	s_or_b64 s[18:19], s[20:21], s[18:19]
	v_cmp_lt_i32_e64 s[14:15], 39, v2
	s_or_b64 s[16:17], s[18:19], s[16:17]
	v_cmp_lt_i32_e64 s[12:13], 34, v2
	s_or_b64 s[14:15], s[16:17], s[14:15]
	v_cmp_lt_i32_e64 s[10:11], 33, v2
	s_or_b64 s[12:13], s[14:15], s[12:13]
	v_cmp_lt_i32_e64 s[8:9], 32, v2
	s_or_b64 s[10:11], s[12:13], s[10:11]
	v_cmp_lt_i32_e32 vcc, 31, v2
	s_or_b64 s[8:9], s[10:11], s[8:9]
	s_or_b64 vcc, s[8:9], vcc
	v_cndmask_b32_e64 v113, v191, v113, s[68:69]
	v_cndmask_b32_e64 v112, v191, v112, s[66:67]
	v_cndmask_b32_e64 v111, v191, v111, s[64:65]
	v_cndmask_b32_e64 v110, v191, v110, s[62:63]
	v_cndmask_b32_e64 v109, v191, v109, s[60:61]
	v_cndmask_b32_e64 v108, v191, v108, s[58:59]
	v_cndmask_b32_e64 v107, v191, v107, s[56:57]
	v_cndmask_b32_e64 v106, v191, v106, s[54:55]
	v_cndmask_b32_e64 v105, v191, v105, s[52:53]
	v_cndmask_b32_e64 v104, v191, v104, s[50:51]
	v_cndmask_b32_e64 v103, v191, v103, s[48:49]
	v_cndmask_b32_e64 v102, v191, v102, s[46:47]
	v_cndmask_b32_e64 v101, v191, v101, s[44:45]
	v_cndmask_b32_e64 v100, v191, v100, s[42:43]
	v_cndmask_b32_e64 v99, v191, v99, s[40:41]
	v_cndmask_b32_e64 v97, v191, v97, s[38:39]
	v_cndmask_b32_e64 v96, v191, v96, s[36:37]
	v_cndmask_b32_e64 v95, v191, v95, s[34:35]
	v_cndmask_b32_e64 v94, v191, v94, s[30:31]
	v_cndmask_b32_e64 v93, v191, v93, s[28:29]
	v_cndmask_b32_e64 v92, v191, v92, s[26:27]
	v_cndmask_b32_e64 v91, v191, v91, s[24:25]
	v_cndmask_b32_e64 v90, v191, v90, s[22:23]
	v_cndmask_b32_e64 v89, v191, v89, s[20:21]
	v_cndmask_b32_e64 v88, v191, v88, s[18:19]
	v_cndmask_b32_e64 v87, v191, v87, s[16:17]
	v_cndmask_b32_e64 v86, v191, v86, s[14:15]
	v_cndmask_b32_e64 v85, v191, v85, s[12:13]
	v_cndmask_b32_e64 v84, v191, v84, s[10:11]
	v_cndmask_b32_e64 v83, v191, v83, s[8:9]
	v_cndmask_b32_e32 v82, v191, v82, vcc

.LBB0_1748:
	s_add_i32 s2, s22, 0x80
	v_mul_f32_e32 v17, 0xbe0293ee, v166
	s_min_i32 s24, s2, s20
	v_fmamk_f32 v12, v98, 0x3e0293ee, v17
	v_fmamk_f32 v13, v99, 0x3e0293ee, v17
	s_waitcnt vmcnt(3)
	ds_write_b128 v188, v[146:149] offset:49152
	s_waitcnt vmcnt(2)
	ds_write_b128 v188, v[150:153] offset:57344
	v_or_b32_e32 v212, s24, v178
	v_fmamk_f32 v14, v100, 0x3e0293ee, v17
	v_fmamk_f32 v15, v101, 0x3e0293ee, v17
	v_fmamk_f32 v98, v102, 0x3e0293ee, v17
	v_fmamk_f32 v99, v103, 0x3e0293ee, v17
	v_fmamk_f32 v102, v106, 0x3e0293ee, v17
	v_fmamk_f32 v103, v107, 0x3e0293ee, v17
	v_fmamk_f32 v106, v110, 0x3e0293ee, v17
	v_fmamk_f32 v107, v111, 0x3e0293ee, v17
	v_fmamk_f32 v82, v82, 0x3e0293ee, v17
	v_fmamk_f32 v83, v83, 0x3e0293ee, v17
	v_exp_f32_e32 v110, v12
	v_exp_f32_e32 v111, v13
	s_waitcnt lgkmcnt(0)
	s_barrier
	v_mad_i64_i32 v[12:13], s[8:9], v212, s3, v[164:165]
	v_add_u32_e32 v213, s24, v179
	v_fmamk_f32 v100, v104, 0x3e0293ee, v17
	v_fmamk_f32 v101, v105, 0x3e0293ee, v17
	v_fmamk_f32 v104, v108, 0x3e0293ee, v17
	v_fmamk_f32 v105, v109, 0x3e0293ee, v17
	v_fmamk_f32 v108, v112, 0x3e0293ee, v17
	v_fmamk_f32 v109, v113, 0x3e0293ee, v17
	v_exp_f32_e32 v112, v14
	v_exp_f32_e32 v113, v15
	v_exp_f32_e32 v175, v82
	v_exp_f32_e32 v195, v83
	v_mad_i64_i32 v[82:83], s[8:9], v213, s3, v[164:165]
	global_load_dwordx4 v[12:15], v[12:13], off
	s_nop 0
	global_load_dwordx4 v[146:149], v[82:83], off
	v_exp_f32_e32 v98, v98
	v_add_f32_e32 v82, 0, v110
	v_exp_f32_e32 v99, v99
	v_add_f32_e32 v82, v111, v82
	v_exp_f32_e32 v100, v100
	v_add_f32_e32 v82, v112, v82
	v_exp_f32_e32 v101, v101
	v_add_f32_e32 v82, v113, v82
	v_exp_f32_e32 v102, v102
	v_add_f32_e32 v82, v98, v82
	v_exp_f32_e32 v103, v103
	v_add_f32_e32 v82, v99, v82
	v_exp_f32_e32 v104, v104
	v_add_f32_e32 v82, v100, v82
	v_exp_f32_e32 v105, v105
	v_add_f32_e32 v82, v101, v82
	v_exp_f32_e32 v106, v106
	v_add_f32_e32 v82, v102, v82
	v_exp_f32_e32 v107, v107
	v_add_f32_e32 v82, v103, v82
	v_exp_f32_e32 v108, v108
	v_add_f32_e32 v82, v104, v82
	v_exp_f32_e32 v109, v109
	v_add_f32_e32 v82, v105, v82
	v_add_f32_e32 v82, v106, v82
	v_fmamk_f32 v84, v84, 0x3e0293ee, v17
	v_add_f32_e32 v82, v107, v82
	v_fmamk_f32 v85, v85, 0x3e0293ee, v17
	v_exp_f32_e32 v196, v84
	v_add_f32_e32 v82, v108, v82
	v_fmamk_f32 v86, v86, 0x3e0293ee, v17
	v_exp_f32_e32 v197, v85
	v_add_f32_e32 v82, v109, v82
	v_fmamk_f32 v87, v87, 0x3e0293ee, v17
	v_exp_f32_e32 v150, v86
	v_add_f32_e32 v82, v175, v82
	v_fmamk_f32 v88, v88, 0x3e0293ee, v17
	v_exp_f32_e32 v151, v87
	v_add_f32_e32 v82, v195, v82
	v_fmamk_f32 v89, v89, 0x3e0293ee, v17
	v_exp_f32_e32 v152, v88
	v_add_f32_e32 v82, v196, v82
	v_fmamk_f32 v90, v90, 0x3e0293ee, v17
	v_exp_f32_e32 v153, v89
	v_add_f32_e32 v82, v197, v82
	v_fmamk_f32 v91, v91, 0x3e0293ee, v17
	v_exp_f32_e32 v198, v90
	v_add_f32_e32 v82, v150, v82
	v_fmamk_f32 v92, v92, 0x3e0293ee, v17
	v_exp_f32_e32 v199, v91
	v_add_f32_e32 v82, v151, v82
	v_fmamk_f32 v93, v93, 0x3e0293ee, v17
	v_exp_f32_e32 v200, v92
	v_add_f32_e32 v82, v152, v82
	v_fmamk_f32 v94, v94, 0x3e0293ee, v17
	v_exp_f32_e32 v201, v93
	v_add_f32_e32 v82, v153, v82
	v_fmamk_f32 v95, v95, 0x3e0293ee, v17
	v_exp_f32_e32 v202, v94
	v_add_f32_e32 v82, v198, v82
	v_fmamk_f32 v96, v96, 0x3e0293ee, v17
	v_exp_f32_e32 v203, v95
	v_add_f32_e32 v82, v199, v82
	v_fmamk_f32 v97, v97, 0x3e0293ee, v17
	v_exp_f32_e32 v204, v96
	v_add_f32_e32 v82, v200, v82
	v_exp_f32_e32 v97, v97
	v_add_f32_e32 v82, v201, v82
	v_add_f32_e32 v82, v202, v82
	v_add_f32_e32 v82, v203, v82
	v_add_f32_e32 v82, v204, v82
	v_add_f32_e32 v169, v97, v82
	v_mov_b32_e32 v174, v169
	v_cvt_pk_bf16_f32 v82, v110, v111
	v_cvt_pk_bf16_f32 v83, v112, v113
	v_cvt_pk_bf16_f32 v84, v98, v99
	v_cvt_pk_bf16_f32 v85, v100, v101
	v_cvt_pk_bf16_f32 v86, v102, v103
	v_cvt_pk_bf16_f32 v87, v104, v105
	v_cvt_pk_bf16_f32 v88, v106, v107
	v_cvt_pk_bf16_f32 v89, v108, v109
	v_cvt_pk_bf16_f32 v90, v175, v195
	v_cvt_pk_bf16_f32 v91, v196, v197
	v_cvt_pk_bf16_f32 v92, v150, v151
	v_cvt_pk_bf16_f32 v93, v152, v153
	v_cvt_pk_bf16_f32 v94, v198, v199
	v_cvt_pk_bf16_f32 v95, v200, v201
	v_cvt_pk_bf16_f32 v96, v202, v203
	v_cvt_pk_bf16_f32 v97, v204, v97
	s_nop 1
	v_permlane32_swap_b32_e32 v169, v174
	v_permlane32_swap_b32_e32 v82, v84
	v_permlane32_swap_b32_e32 v83, v85
	v_permlane32_swap_b32_e32 v86, v88
	v_permlane32_swap_b32_e32 v87, v89
	v_permlane32_swap_b32_e32 v90, v92
	v_permlane32_swap_b32_e32 v91, v93
	v_permlane32_swap_b32_e32 v94, v96
	v_permlane32_swap_b32_e32 v95, v97
	ds_read_b64_tr_b16 v[98:99], v180 offset:0
	ds_read_b64_tr_b16 v[100:101], v180 offset:0x800
	ds_read_b64_tr_b16 v[102:103], v180 offset:0x1000
	ds_read_b64_tr_b16 v[104:105], v180 offset:0x1800
	ds_read_b64_tr_b16 v[106:107], v180 offset:0x2000
	ds_read_b64_tr_b16 v[108:109], v180 offset:0x2800
	ds_read_b64_tr_b16 v[110:111], v180 offset:0x3000
	ds_read_b64_tr_b16 v[112:113], v180 offset:0x3800
	ds_read_b64_tr_b16 v[150:151], v180 offset:0x200
	ds_read_b64_tr_b16 v[152:153], v180 offset:0xa00
	ds_read_b64_tr_b16 v[196:197], v180 offset:0x1200
	ds_read_b64_tr_b16 v[198:199], v180 offset:0x1a00
	ds_read_b64_tr_b16 v[200:201], v180 offset:0x2200
	ds_read_b64_tr_b16 v[202:203], v180 offset:0x2a00
	ds_read_b64_tr_b16 v[204:205], v180 offset:0x3200
	ds_read_b64_tr_b16 v[206:207], v180 offset:0x3a00
	s_waitcnt lgkmcnt(8)
	s_nop 0
	v_mfma_f32_32x32x16_bf16 v[66:81], v[82:85], v[98:101], v[66:81]
	ds_read_b64_tr_b16 v[98:99], v180 offset:0x400
	ds_read_b64_tr_b16 v[100:101], v180 offset:0xc00
	v_mfma_f32_32x32x16_bf16 v[66:81], v[86:89], v[102:105], v[66:81]
	ds_read_b64_tr_b16 v[102:103], v180 offset:0x1400
	ds_read_b64_tr_b16 v[104:105], v180 offset:0x1c00
	v_mfma_f32_32x32x16_bf16 v[66:81], v[90:93], v[106:109], v[66:81]
	ds_read_b64_tr_b16 v[106:107], v180 offset:0x2400
	ds_read_b64_tr_b16 v[108:109], v180 offset:0x2c00
	ds_read_b64_tr_b16 v[208:209], v180 offset:0x3400
	ds_read_b64_tr_b16 v[210:211], v180 offset:0x3c00
	s_waitcnt lgkmcnt(8)
	v_mfma_f32_32x32x16_bf16 v[66:81], v[94:97], v[110:113], v[66:81]
	v_mfma_f32_32x32x16_bf16 v[50:65], v[82:85], v[150:153], v[50:65]
	ds_read_b64_tr_b16 v[110:111], v180 offset:0x600
	ds_read_b64_tr_b16 v[112:113], v180 offset:0xe00
	ds_read_b64_tr_b16 v[150:151], v180 offset:0x1600
	ds_read_b64_tr_b16 v[152:153], v180 offset:0x1e00
	v_mfma_f32_32x32x16_bf16 v[50:65], v[86:89], v[196:199], v[50:65]
	ds_read_b64_tr_b16 v[196:197], v180 offset:0x2600
	ds_read_b64_tr_b16 v[198:199], v180 offset:0x2e00
	v_mfma_f32_32x32x16_bf16 v[50:65], v[90:93], v[200:203], v[50:65]
	ds_read_b64_tr_b16 v[200:201], v180 offset:0x3600
	ds_read_b64_tr_b16 v[202:203], v180 offset:0x3e00
	s_waitcnt lgkmcnt(8)
	v_mfma_f32_32x32x16_bf16 v[50:65], v[94:97], v[204:207], v[50:65]
	v_mfma_f32_32x32x16_bf16 v[34:49], v[82:85], v[98:101], v[34:49]
	s_waitcnt lgkmcnt(0)
	v_mfma_f32_32x32x16_bf16 v[34:49], v[86:89], v[102:105], v[34:49]
	v_mfma_f32_32x32x16_bf16 v[34:49], v[90:93], v[106:109], v[34:49]
	v_mfma_f32_32x32x16_bf16 v[34:49], v[94:97], v[208:211], v[34:49]
	s_waitcnt vmcnt(3)
	ds_write_b128 v189, v[4:7] offset:16384
	s_waitcnt vmcnt(2)
	ds_write_b128 v190, v[8:11] offset:16384
	s_waitcnt lgkmcnt(0)
	s_barrier
	v_mfma_f32_32x32x16_bf16 v[18:33], v[82:85], v[110:113], v[18:33]
	v_mfma_f32_32x32x16_bf16 v[18:33], v[86:89], v[150:153], v[18:33]
	v_mfma_f32_32x32x16_bf16 v[18:33], v[90:93], v[196:199], v[18:33]
	v_mfma_f32_32x32x16_bf16 v[18:33], v[94:97], v[200:203], v[18:33]
	v_mad_i64_i32 v[4:5], s[8:9], v212, s3, v[162:163]
	v_mad_i64_i32 v[8:9], s[8:9], v213, s3, v[162:163]
	global_load_dwordx4 v[4:7], v[4:5], off
	s_nop 0
	global_load_dwordx4 v[8:11], v[8:9], off
	ds_read_b128 v[82:85], v171 offset:49152
	ds_read_b128 v[86:89], v171 offset:57344
	ds_read_b128 v[150:153], v170 offset:49152
	ds_read_b128 v[196:199], v170 offset:57344
	ds_read_b128 v[200:203], v157 offset:49152
	ds_read_b128 v[204:207], v157 offset:57344
	ds_read_b128 v[208:211], v155 offset:49152
	ds_read_b128 v[212:215], v155 offset:57344
	ds_read_b128 v[216:219], v171 offset:49280
	ds_read_b128 v[220:223], v171 offset:57472
	ds_read_b128 v[224:227], v170 offset:49280
	ds_read_b128 v[228:231], v170 offset:57472
	s_waitcnt lgkmcnt(11)
	v_mfma_f32_32x32x16_bf16 v[98:113], v[82:85], v[142:145], 0
	s_waitcnt lgkmcnt(10)
	v_mfma_f32_32x32x16_bf16 v[82:97], v[86:89], v[142:145], 0
	s_waitcnt lgkmcnt(9)
	v_mfma_f32_32x32x16_bf16 v[98:113], v[150:153], v[138:141], v[98:113]
	s_waitcnt lgkmcnt(8)
	v_mfma_f32_32x32x16_bf16 v[82:97], v[196:199], v[138:141], v[82:97]
	ds_read_b128 v[150:153], v157 offset:49280
	ds_read_b128 v[196:199], v157 offset:57472
	ds_read_b128 v[232:235], v155 offset:49280
	ds_read_b128 v[236:239], v155 offset:57472
	s_waitcnt lgkmcnt(11)
	v_mfma_f32_32x32x16_bf16 v[98:113], v[200:203], v[134:137], v[98:113]
	s_waitcnt lgkmcnt(10)
	v_mfma_f32_32x32x16_bf16 v[82:97], v[204:207], v[134:137], v[82:97]
	s_waitcnt lgkmcnt(9)
	v_mfma_f32_32x32x16_bf16 v[98:113], v[208:211], v[130:133], v[98:113]
	s_waitcnt lgkmcnt(8)
	v_mfma_f32_32x32x16_bf16 v[82:97], v[212:215], v[130:133], v[82:97]
	s_waitcnt lgkmcnt(7)
	v_mfma_f32_32x32x16_bf16 v[98:113], v[216:219], v[126:129], v[98:113]
	s_add_i32 s8, s22, 0x7f
	s_cmp_le_u32 s8, s79
	s_cselect_b64 s[8:9], -1, 0
	s_cmp_gt_i32 s23, s10
	s_cselect_b64 s[24:25], -1, 0
	s_and_b64 s[8:9], s[8:9], s[24:25]
	s_and_b64 vcc, exec, s[8:9]
	s_waitcnt lgkmcnt(6)
	v_mfma_f32_32x32x16_bf16 v[82:97], v[220:223], v[126:129], v[82:97]
	s_waitcnt lgkmcnt(5)
	v_mfma_f32_32x32x16_bf16 v[98:113], v[224:227], v[122:125], v[98:113]
	s_waitcnt lgkmcnt(4)
	v_mfma_f32_32x32x16_bf16 v[82:97], v[228:231], v[122:125], v[82:97]
	s_waitcnt lgkmcnt(3)
	v_mfma_f32_32x32x16_bf16 v[98:113], v[150:153], v[118:121], v[98:113]
	s_waitcnt lgkmcnt(2)
	v_mfma_f32_32x32x16_bf16 v[82:97], v[196:199], v[118:121], v[82:97]
	s_waitcnt lgkmcnt(1)
	v_mfma_f32_32x32x16_bf16 v[98:113], v[232:235], v[114:117], v[98:113]
	s_waitcnt lgkmcnt(0)
	v_mfma_f32_32x32x16_bf16 v[82:97], v[236:239], v[114:117], v[82:97]
	s_cbranch_vccnz .LBB0_1750
	v_subrev_u32_e32 v150, 64, v16
	v_cmp_gt_u32_e32 vcc, s77, v150
	v_add_u32_e32 v150, 0xffffffa0, v16
	s_nop 5
	v_cndmask_b32_e32 v98, v191, v98, vcc
	v_cmp_gt_u32_e32 vcc, s77, v150
	v_add_u32_e32 v150, 0xffffffbf, v16
	s_nop 0
	v_cndmask_b32_e32 v82, v191, v82, vcc
	v_cmp_gt_u32_e32 vcc, s77, v150
	v_add_u32_e32 v150, 0xffffff9f, v16
	s_nop 0
	v_cndmask_b32_e32 v99, v191, v99, vcc
	v_cmp_gt_u32_e32 vcc, s77, v150
	v_add_u32_e32 v150, 0xffffffbe, v16
	s_nop 0
	v_cndmask_b32_e32 v83, v191, v83, vcc
	v_cmp_gt_u32_e32 vcc, s77, v150
	v_add_u32_e32 v150, 0xffffff9e, v16
	s_nop 0
	v_cndmask_b32_e32 v100, v191, v100, vcc
	v_cmp_gt_u32_e32 vcc, s77, v150
	v_add_u32_e32 v150, 0xffffffbd, v16
	s_nop 0
	v_cndmask_b32_e32 v84, v191, v84, vcc
	v_cmp_gt_u32_e32 vcc, s77, v150
	v_add_u32_e32 v150, 0xffffff9d, v16
	s_nop 0
	v_cndmask_b32_e32 v101, v191, v101, vcc
	v_cmp_gt_u32_e32 vcc, s77, v150
	v_add_u32_e32 v150, 0xffffffb8, v16
	s_nop 0
	v_cndmask_b32_e32 v85, v191, v85, vcc
	v_cmp_gt_u32_e32 vcc, s77, v150
	v_add_u32_e32 v150, 0xffffff98, v16
	s_nop 0
	v_cndmask_b32_e32 v102, v191, v102, vcc
	v_cmp_gt_u32_e32 vcc, s77, v150
	v_add_u32_e32 v150, 0xffffffb7, v16
	s_nop 0
	v_cndmask_b32_e32 v86, v191, v86, vcc
	v_cmp_gt_u32_e32 vcc, s77, v150
	v_add_u32_e32 v150, 0xffffff97, v16
	s_nop 0
	v_cndmask_b32_e32 v103, v191, v103, vcc
	v_cmp_gt_u32_e32 vcc, s77, v150
	v_add_u32_e32 v150, 0xffffffb6, v16
	s_nop 0
	v_cndmask_b32_e32 v87, v191, v87, vcc
	v_cmp_gt_u32_e32 vcc, s77, v150
	v_add_u32_e32 v150, 0xffffff96, v16
	s_nop 0
	v_cndmask_b32_e32 v104, v191, v104, vcc
	v_cmp_gt_u32_e32 vcc, s77, v150
	v_add_u32_e32 v150, 0xffffffb5, v16
	s_nop 0
	v_cndmask_b32_e32 v88, v191, v88, vcc
	v_cmp_gt_u32_e32 vcc, s77, v150
	v_add_u32_e32 v150, 0xffffff95, v16
	s_nop 0
	v_cndmask_b32_e32 v105, v191, v105, vcc
	v_cmp_gt_u32_e32 vcc, s77, v150
	v_add_u32_e32 v150, 0xffffffb0, v16
	s_nop 0
	v_cndmask_b32_e32 v89, v191, v89, vcc
	v_cmp_gt_u32_e32 vcc, s77, v150
	v_add_u32_e32 v150, 0xffffff90, v16
	s_nop 0
	v_cndmask_b32_e32 v106, v191, v106, vcc
	v_cmp_gt_u32_e32 vcc, s77, v150
	v_add_u32_e32 v150, 0xffffffaf, v16
	s_nop 0
	v_cndmask_b32_e32 v90, v191, v90, vcc
	v_cmp_gt_u32_e32 vcc, s77, v150
	v_add_u32_e32 v150, 0xffffff8f, v16
	s_nop 0
	v_cndmask_b32_e32 v107, v191, v107, vcc
	v_cmp_gt_u32_e32 vcc, s77, v150
	v_add_u32_e32 v150, 0xffffffae, v16
	s_nop 0
	v_cndmask_b32_e32 v91, v191, v91, vcc
	v_cmp_gt_u32_e32 vcc, s77, v150
	v_add_u32_e32 v150, 0xffffff8e, v16
	s_nop 0
	v_cndmask_b32_e32 v108, v191, v108, vcc
	v_cmp_gt_u32_e32 vcc, s77, v150
	v_add_u32_e32 v150, 0xffffffad, v16
	s_nop 0
	v_cndmask_b32_e32 v92, v191, v92, vcc
	v_cmp_gt_u32_e32 vcc, s77, v150
	v_add_u32_e32 v150, 0xffffff8d, v16
	s_nop 0
	v_cndmask_b32_e32 v109, v191, v109, vcc
	v_cmp_gt_u32_e32 vcc, s77, v150
	v_add_u32_e32 v150, 0xffffffa8, v16
	s_nop 0
	v_cndmask_b32_e32 v93, v191, v93, vcc
	v_cmp_gt_u32_e32 vcc, s77, v150
	v_add_u32_e32 v150, 0xffffff88, v16
	s_nop 0
	v_cndmask_b32_e32 v110, v191, v110, vcc
	v_cmp_gt_u32_e32 vcc, s77, v150
	v_add_u32_e32 v150, 0xffffffa7, v16
	s_nop 0
	v_cndmask_b32_e32 v94, v191, v94, vcc
	v_cmp_gt_u32_e32 vcc, s77, v150
	v_add_u32_e32 v150, 0xffffff87, v16
	s_nop 0
	v_cndmask_b32_e32 v111, v191, v111, vcc
	v_cmp_gt_u32_e32 vcc, s77, v150
	v_add_u32_e32 v150, 0xffffffa6, v16
	s_nop 0
	v_cndmask_b32_e32 v95, v191, v95, vcc
	v_cmp_gt_u32_e32 vcc, s77, v150
	v_add_u32_e32 v150, 0xffffff86, v16
	s_nop 0
	v_cndmask_b32_e32 v112, v191, v112, vcc
	v_cmp_gt_u32_e32 vcc, s77, v150
	v_add_u32_e32 v150, 0xffffffa5, v16
	v_add_u32_e32 v16, 0xffffff85, v16
	v_cndmask_b32_e32 v96, v191, v96, vcc
	v_cmp_gt_u32_e32 vcc, s77, v150
	s_nop 1
	v_cndmask_b32_e32 v113, v191, v113, vcc
	v_cmp_gt_u32_e32 vcc, s77, v16
	s_nop 1
	v_cndmask_b32_e32 v97, v191, v97, vcc

.LBB0_1916:
	v_lshrrev_b64 v[12:13], s10, v[164:165]
	v_and_b32_e32 v12, 1, v12
	v_mul_f32_e32 v17, 0xbe0293ee, v161
	v_cmp_eq_u32_e32 vcc, 1, v12
	s_sub_i32 s2, s18, 64
	s_min_i32 s2, s2, s5
	v_cndmask_b32_e32 v175, v191, v17, vcc
	v_fmamk_f32 v12, v98, 0x3e0293ee, v175
	v_fmamk_f32 v13, v99, 0x3e0293ee, v175
	s_waitcnt vmcnt(3)
	ds_write_b128 v188, v[146:149] offset:49152
	s_waitcnt vmcnt(2)
	ds_write_b128 v188, v[150:153] offset:57344
	v_or_b32_e32 v212, s2, v178
	v_fmamk_f32 v14, v100, 0x3e0293ee, v175
	v_fmamk_f32 v15, v101, 0x3e0293ee, v175
	v_fmamk_f32 v98, v102, 0x3e0293ee, v175
	v_fmamk_f32 v99, v103, 0x3e0293ee, v175
	v_fmamk_f32 v100, v104, 0x3e0293ee, v175
	v_fmamk_f32 v101, v105, 0x3e0293ee, v175
	v_fmamk_f32 v102, v106, 0x3e0293ee, v175
	v_fmamk_f32 v103, v107, 0x3e0293ee, v175
	v_fmamk_f32 v104, v108, 0x3e0293ee, v175
	v_fmamk_f32 v105, v109, 0x3e0293ee, v175
	v_fmamk_f32 v106, v110, 0x3e0293ee, v175
	v_fmamk_f32 v107, v111, 0x3e0293ee, v175
	v_fmamk_f32 v108, v112, 0x3e0293ee, v175
	v_fmamk_f32 v109, v113, 0x3e0293ee, v175
	v_fmamk_f32 v82, v82, 0x3e0293ee, v175
	v_fmamk_f32 v83, v83, 0x3e0293ee, v175
	v_fmamk_f32 v84, v84, 0x3e0293ee, v175
	v_fmamk_f32 v85, v85, 0x3e0293ee, v175
	v_fmamk_f32 v86, v86, 0x3e0293ee, v175
	v_fmamk_f32 v87, v87, 0x3e0293ee, v175
	v_fmamk_f32 v88, v88, 0x3e0293ee, v175
	v_fmamk_f32 v89, v89, 0x3e0293ee, v175
	v_fmamk_f32 v90, v90, 0x3e0293ee, v175
	v_fmamk_f32 v91, v91, 0x3e0293ee, v175
	v_fmamk_f32 v92, v92, 0x3e0293ee, v175
	v_fmamk_f32 v93, v93, 0x3e0293ee, v175
	v_fmamk_f32 v94, v94, 0x3e0293ee, v175
	v_fmamk_f32 v95, v95, 0x3e0293ee, v175
	v_fmamk_f32 v96, v96, 0x3e0293ee, v175
	v_fmac_f32_e32 v175, 0x3e0293ee, v97
	v_exp_f32_e32 v97, v12
	v_exp_f32_e32 v110, v13
	s_waitcnt lgkmcnt(0)
	s_barrier
	v_mad_i64_i32 v[12:13], s[12:13], v212, s3, v[168:169]
	v_add_u32_e32 v213, s2, v179
	v_exp_f32_e32 v111, v14
	v_exp_f32_e32 v112, v15
	v_exp_f32_e32 v113, v82
	v_exp_f32_e32 v196, v83
	v_mad_i64_i32 v[82:83], s[12:13], v213, s3, v[168:169]
	global_load_dwordx4 v[12:15], v[12:13], off
	s_nop 0
	global_load_dwordx4 v[146:149], v[82:83], off
	v_exp_f32_e32 v98, v98
	v_add_f32_e32 v82, 0, v97
	v_exp_f32_e32 v99, v99
	v_add_f32_e32 v82, v110, v82
	v_exp_f32_e32 v100, v100
	v_add_f32_e32 v82, v111, v82
	v_exp_f32_e32 v101, v101
	v_add_f32_e32 v82, v112, v82
	v_exp_f32_e32 v102, v102
	v_add_f32_e32 v82, v98, v82
	v_exp_f32_e32 v103, v103
	v_add_f32_e32 v82, v99, v82
	v_exp_f32_e32 v104, v104
	v_add_f32_e32 v82, v100, v82
	v_exp_f32_e32 v105, v105
	v_add_f32_e32 v82, v101, v82
	v_exp_f32_e32 v106, v106
	v_add_f32_e32 v82, v102, v82
	v_exp_f32_e32 v107, v107
	v_add_f32_e32 v82, v103, v82
	v_exp_f32_e32 v108, v108
	v_add_f32_e32 v82, v104, v82
	v_exp_f32_e32 v109, v109
	v_add_f32_e32 v82, v105, v82
	v_add_f32_e32 v82, v106, v82
	v_add_f32_e32 v82, v107, v82
	v_exp_f32_e32 v197, v84
	v_add_f32_e32 v82, v108, v82
	v_exp_f32_e32 v198, v85
	v_add_f32_e32 v82, v109, v82
	v_exp_f32_e32 v150, v86
	v_add_f32_e32 v82, v113, v82
	v_exp_f32_e32 v151, v87
	v_add_f32_e32 v82, v196, v82
	v_exp_f32_e32 v152, v88
	v_add_f32_e32 v82, v197, v82
	v_exp_f32_e32 v153, v89
	v_add_f32_e32 v82, v198, v82
	v_exp_f32_e32 v199, v90
	v_add_f32_e32 v82, v150, v82
	v_exp_f32_e32 v200, v91
	v_add_f32_e32 v82, v151, v82
	v_exp_f32_e32 v201, v92
	v_add_f32_e32 v82, v152, v82
	v_exp_f32_e32 v202, v93
	v_add_f32_e32 v82, v153, v82
	v_exp_f32_e32 v203, v94
	v_add_f32_e32 v82, v199, v82
	v_exp_f32_e32 v204, v95
	v_add_f32_e32 v82, v200, v82
	v_exp_f32_e32 v205, v96
	v_add_f32_e32 v82, v201, v82
	v_exp_f32_e32 v206, v175
	v_add_f32_e32 v82, v202, v82
	v_add_f32_e32 v82, v203, v82
	v_add_f32_e32 v82, v204, v82
	v_add_f32_e32 v82, v205, v82
	v_add_f32_e32 v175, v206, v82
	v_mov_b32_e32 v195, v175
	v_cvt_pk_bf16_f32 v82, v97, v110
	v_cvt_pk_bf16_f32 v83, v111, v112
	v_cvt_pk_bf16_f32 v84, v98, v99
	v_cvt_pk_bf16_f32 v85, v100, v101
	v_cvt_pk_bf16_f32 v86, v102, v103
	v_cvt_pk_bf16_f32 v87, v104, v105
	v_cvt_pk_bf16_f32 v88, v106, v107
	v_cvt_pk_bf16_f32 v89, v108, v109
	v_cvt_pk_bf16_f32 v90, v113, v196
	v_cvt_pk_bf16_f32 v91, v197, v198
	v_cvt_pk_bf16_f32 v92, v150, v151
	v_cvt_pk_bf16_f32 v93, v152, v153
	v_cvt_pk_bf16_f32 v94, v199, v200
	v_cvt_pk_bf16_f32 v95, v201, v202
	v_cvt_pk_bf16_f32 v96, v203, v204
	v_cvt_pk_bf16_f32 v97, v205, v206
	s_nop 1
	v_permlane32_swap_b32_e32 v175, v195
	v_permlane32_swap_b32_e32 v82, v84
	v_permlane32_swap_b32_e32 v83, v85
	v_permlane32_swap_b32_e32 v86, v88
	v_permlane32_swap_b32_e32 v87, v89
	v_permlane32_swap_b32_e32 v90, v92
	v_permlane32_swap_b32_e32 v91, v93
	v_permlane32_swap_b32_e32 v94, v96
	v_permlane32_swap_b32_e32 v95, v97
	ds_read_b64_tr_b16 v[98:99], v180 offset:0
	ds_read_b64_tr_b16 v[100:101], v180 offset:0x800
	ds_read_b64_tr_b16 v[102:103], v180 offset:0x1000
	ds_read_b64_tr_b16 v[104:105], v180 offset:0x1800
	ds_read_b64_tr_b16 v[106:107], v180 offset:0x2000
	ds_read_b64_tr_b16 v[108:109], v180 offset:0x2800
	ds_read_b64_tr_b16 v[110:111], v180 offset:0x3000
	ds_read_b64_tr_b16 v[112:113], v180 offset:0x3800
	ds_read_b64_tr_b16 v[150:151], v180 offset:0x200
	ds_read_b64_tr_b16 v[152:153], v180 offset:0xa00
	ds_read_b64_tr_b16 v[196:197], v180 offset:0x1200
	ds_read_b64_tr_b16 v[198:199], v180 offset:0x1a00
	ds_read_b64_tr_b16 v[200:201], v180 offset:0x2200
	ds_read_b64_tr_b16 v[202:203], v180 offset:0x2a00
	ds_read_b64_tr_b16 v[204:205], v180 offset:0x3200
	ds_read_b64_tr_b16 v[206:207], v180 offset:0x3a00
	s_waitcnt lgkmcnt(8)
	s_nop 0
	v_mfma_f32_32x32x16_bf16 v[66:81], v[82:85], v[98:101], v[66:81]
	ds_read_b64_tr_b16 v[98:99], v180 offset:0x400
	ds_read_b64_tr_b16 v[100:101], v180 offset:0xc00
	v_mfma_f32_32x32x16_bf16 v[66:81], v[86:89], v[102:105], v[66:81]
	ds_read_b64_tr_b16 v[102:103], v180 offset:0x1400
	ds_read_b64_tr_b16 v[104:105], v180 offset:0x1c00
	v_mfma_f32_32x32x16_bf16 v[66:81], v[90:93], v[106:109], v[66:81]
	ds_read_b64_tr_b16 v[106:107], v180 offset:0x2400
	ds_read_b64_tr_b16 v[108:109], v180 offset:0x2c00
	ds_read_b64_tr_b16 v[208:209], v180 offset:0x3400
	ds_read_b64_tr_b16 v[210:211], v180 offset:0x3c00
	s_waitcnt lgkmcnt(8)
	v_mfma_f32_32x32x16_bf16 v[66:81], v[94:97], v[110:113], v[66:81]
	v_mfma_f32_32x32x16_bf16 v[50:65], v[82:85], v[150:153], v[50:65]
	ds_read_b64_tr_b16 v[110:111], v180 offset:0x600
	ds_read_b64_tr_b16 v[112:113], v180 offset:0xe00
	ds_read_b64_tr_b16 v[150:151], v180 offset:0x1600
	ds_read_b64_tr_b16 v[152:153], v180 offset:0x1e00
	v_mfma_f32_32x32x16_bf16 v[50:65], v[86:89], v[196:199], v[50:65]
	ds_read_b64_tr_b16 v[196:197], v180 offset:0x2600
	ds_read_b64_tr_b16 v[198:199], v180 offset:0x2e00
	v_mfma_f32_32x32x16_bf16 v[50:65], v[90:93], v[200:203], v[50:65]
	ds_read_b64_tr_b16 v[200:201], v180 offset:0x3600
	ds_read_b64_tr_b16 v[202:203], v180 offset:0x3e00
	s_waitcnt lgkmcnt(8)
	v_mfma_f32_32x32x16_bf16 v[50:65], v[94:97], v[204:207], v[50:65]
	v_mfma_f32_32x32x16_bf16 v[34:49], v[82:85], v[98:101], v[34:49]
	s_waitcnt lgkmcnt(0)
	v_mfma_f32_32x32x16_bf16 v[34:49], v[86:89], v[102:105], v[34:49]
	v_mfma_f32_32x32x16_bf16 v[34:49], v[90:93], v[106:109], v[34:49]
	v_mfma_f32_32x32x16_bf16 v[34:49], v[94:97], v[208:211], v[34:49]
	s_waitcnt vmcnt(3)
	ds_write_b128 v189, v[4:7] offset:16384
	s_waitcnt vmcnt(2)
	ds_write_b128 v190, v[8:11] offset:16384
	s_waitcnt lgkmcnt(0)
	s_barrier
	v_mfma_f32_32x32x16_bf16 v[18:33], v[82:85], v[110:113], v[18:33]
	v_mfma_f32_32x32x16_bf16 v[18:33], v[86:89], v[150:153], v[18:33]
	v_mfma_f32_32x32x16_bf16 v[18:33], v[90:93], v[196:199], v[18:33]
	v_mfma_f32_32x32x16_bf16 v[18:33], v[94:97], v[200:203], v[18:33]
	v_mad_i64_i32 v[4:5], s[12:13], v212, s3, v[166:167]
	v_mad_i64_i32 v[8:9], s[12:13], v213, s3, v[166:167]
	global_load_dwordx4 v[4:7], v[4:5], off
	s_nop 0
	global_load_dwordx4 v[8:11], v[8:9], off
	ds_read_b128 v[82:85], v171 offset:49152
	ds_read_b128 v[86:89], v171 offset:57344
	ds_read_b128 v[150:153], v170 offset:49152
	ds_read_b128 v[196:199], v170 offset:57344
	ds_read_b128 v[200:203], v157 offset:49152
	ds_read_b128 v[204:207], v157 offset:57344
	ds_read_b128 v[208:211], v155 offset:49152
	ds_read_b128 v[212:215], v155 offset:57344
	ds_read_b128 v[216:219], v171 offset:49280
	ds_read_b128 v[220:223], v171 offset:57472
	ds_read_b128 v[224:227], v170 offset:49280
	ds_read_b128 v[228:231], v170 offset:57472
	s_waitcnt lgkmcnt(11)
	v_mfma_f32_32x32x16_bf16 v[98:113], v[82:85], v[142:145], 0
	s_waitcnt lgkmcnt(10)
	v_mfma_f32_32x32x16_bf16 v[82:97], v[86:89], v[142:145], 0
	s_waitcnt lgkmcnt(9)
	v_mfma_f32_32x32x16_bf16 v[98:113], v[150:153], v[138:141], v[98:113]
	s_waitcnt lgkmcnt(8)
	v_mfma_f32_32x32x16_bf16 v[82:97], v[196:199], v[138:141], v[82:97]
	ds_read_b128 v[150:153], v157 offset:49280
	ds_read_b128 v[196:199], v157 offset:57472
	ds_read_b128 v[232:235], v155 offset:49280
	ds_read_b128 v[236:239], v155 offset:57472
	s_waitcnt lgkmcnt(11)
	v_mfma_f32_32x32x16_bf16 v[98:113], v[200:203], v[134:137], v[98:113]
	s_waitcnt lgkmcnt(10)
	v_mfma_f32_32x32x16_bf16 v[82:97], v[204:207], v[134:137], v[82:97]
	s_waitcnt lgkmcnt(9)
	v_mfma_f32_32x32x16_bf16 v[98:113], v[208:211], v[130:133], v[98:113]
	s_waitcnt lgkmcnt(8)
	v_mfma_f32_32x32x16_bf16 v[82:97], v[212:215], v[130:133], v[82:97]
	s_waitcnt lgkmcnt(7)
	v_mfma_f32_32x32x16_bf16 v[98:113], v[216:219], v[126:129], v[98:113]
	s_add_i32 s2, s18, 0xffffffbf
	s_cmp_le_u32 s2, s79
	s_waitcnt lgkmcnt(6)
	v_mfma_f32_32x32x16_bf16 v[82:97], v[220:223], v[126:129], v[82:97]
	s_waitcnt lgkmcnt(5)
	v_mfma_f32_32x32x16_bf16 v[98:113], v[224:227], v[122:125], v[98:113]
	s_waitcnt lgkmcnt(4)
	v_mfma_f32_32x32x16_bf16 v[82:97], v[228:231], v[122:125], v[82:97]
	s_waitcnt lgkmcnt(3)
	v_mfma_f32_32x32x16_bf16 v[98:113], v[150:153], v[118:121], v[98:113]
	s_waitcnt lgkmcnt(2)
	v_mfma_f32_32x32x16_bf16 v[82:97], v[196:199], v[118:121], v[82:97]
	s_waitcnt lgkmcnt(1)
	v_mfma_f32_32x32x16_bf16 v[98:113], v[232:235], v[114:117], v[98:113]
	s_waitcnt lgkmcnt(0)
	v_mfma_f32_32x32x16_bf16 v[82:97], v[236:239], v[114:117], v[82:97]
	s_cbranch_scc1 .LBB0_1918
	v_subrev_u32_e32 v150, 64, v16
	v_cmp_gt_u32_e32 vcc, s82, v150
	v_add_u32_e32 v151, 0xffffffa0, v16
	s_nop 5
	v_cndmask_b32_e32 v98, v191, v98, vcc
	v_cmp_gt_u32_e32 vcc, s82, v151
	s_nop 1
	v_cndmask_b32_e32 v82, v191, v82, vcc
	v_cmp_lt_i32_e32 vcc, 0, v150
	v_add_u32_e32 v150, 0xffffff9f, v16
	s_nop 0
	v_cndmask_b32_e32 v99, v191, v99, vcc
	v_cmp_gt_u32_e32 vcc, s82, v150
	v_add_u32_e32 v150, 0xffffffbe, v16
	s_nop 0
	v_cndmask_b32_e32 v83, v191, v83, vcc
	v_cmp_gt_u32_e32 vcc, s82, v150
	v_add_u32_e32 v150, 0xffffff9e, v16
	s_nop 0
	v_cndmask_b32_e32 v100, v191, v100, vcc
	v_cmp_gt_u32_e32 vcc, s82, v150
	v_add_u32_e32 v150, 0xffffffbd, v16
	s_nop 0
	v_cndmask_b32_e32 v84, v191, v84, vcc
	v_cmp_gt_u32_e32 vcc, s82, v150
	v_add_u32_e32 v150, 0xffffff9d, v16
	s_nop 0
	v_cndmask_b32_e32 v101, v191, v101, vcc
	v_cmp_gt_u32_e32 vcc, s82, v150
	v_add_u32_e32 v150, 0xffffffb8, v16
	s_nop 0
	v_cndmask_b32_e32 v85, v191, v85, vcc
	v_cmp_gt_u32_e32 vcc, s82, v150
	v_add_u32_e32 v150, 0xffffff98, v16
	s_nop 0
	v_cndmask_b32_e32 v102, v191, v102, vcc
	v_cmp_gt_u32_e32 vcc, s82, v150
	v_add_u32_e32 v150, 0xffffffb7, v16
	s_nop 0
	v_cndmask_b32_e32 v86, v191, v86, vcc
	v_cmp_gt_u32_e32 vcc, s82, v150
	v_add_u32_e32 v150, 0xffffff97, v16
	s_nop 0
	v_cndmask_b32_e32 v103, v191, v103, vcc
	v_cmp_gt_u32_e32 vcc, s82, v150
	v_add_u32_e32 v150, 0xffffffb6, v16
	s_nop 0
	v_cndmask_b32_e32 v87, v191, v87, vcc
	v_cmp_gt_u32_e32 vcc, s82, v150
	v_add_u32_e32 v150, 0xffffff96, v16
	s_nop 0
	v_cndmask_b32_e32 v104, v191, v104, vcc
	v_cmp_gt_u32_e32 vcc, s82, v150
	v_add_u32_e32 v150, 0xffffffb5, v16
	s_nop 0
	v_cndmask_b32_e32 v88, v191, v88, vcc
	v_cmp_gt_u32_e32 vcc, s82, v150
	v_add_u32_e32 v150, 0xffffff95, v16
	s_nop 0
	v_cndmask_b32_e32 v105, v191, v105, vcc
	v_cmp_gt_u32_e32 vcc, s82, v150
	v_add_u32_e32 v150, 0xffffffb0, v16
	s_nop 0
	v_cndmask_b32_e32 v89, v191, v89, vcc
	v_cmp_gt_u32_e32 vcc, s82, v150
	v_add_u32_e32 v150, 0xffffff90, v16
	s_nop 0
	v_cndmask_b32_e32 v106, v191, v106, vcc
	v_cmp_gt_u32_e32 vcc, s82, v150
	v_add_u32_e32 v150, 0xffffffaf, v16
	s_nop 0
	v_cndmask_b32_e32 v90, v191, v90, vcc
	v_cmp_gt_u32_e32 vcc, s82, v150
	v_add_u32_e32 v150, 0xffffff8f, v16
	s_nop 0
	v_cndmask_b32_e32 v107, v191, v107, vcc
	v_cmp_gt_u32_e32 vcc, s82, v150
	v_add_u32_e32 v150, 0xffffffae, v16
	s_nop 0
	v_cndmask_b32_e32 v91, v191, v91, vcc
	v_cmp_gt_u32_e32 vcc, s82, v150
	v_add_u32_e32 v150, 0xffffff8e, v16
	s_nop 0
	v_cndmask_b32_e32 v108, v191, v108, vcc
	v_cmp_gt_u32_e32 vcc, s82, v150
	v_add_u32_e32 v150, 0xffffffad, v16
	s_nop 0
	v_cndmask_b32_e32 v92, v191, v92, vcc
	v_cmp_gt_u32_e32 vcc, s82, v150
	v_add_u32_e32 v150, 0xffffff8d, v16
	s_nop 0
	v_cndmask_b32_e32 v109, v191, v109, vcc
	v_cmp_gt_u32_e32 vcc, s82, v150
	v_add_u32_e32 v150, 0xffffffa8, v16
	s_nop 0
	v_cndmask_b32_e32 v93, v191, v93, vcc
	v_cmp_gt_u32_e32 vcc, s82, v150
	v_add_u32_e32 v150, 0xffffff88, v16
	s_nop 0
	v_cndmask_b32_e32 v110, v191, v110, vcc
	v_cmp_gt_u32_e32 vcc, s82, v150
	v_add_u32_e32 v150, 0xffffffa7, v16
	s_nop 0
	v_cndmask_b32_e32 v94, v191, v94, vcc
	v_cmp_gt_u32_e32 vcc, s82, v150
	v_add_u32_e32 v150, 0xffffff87, v16
	s_nop 0
	v_cndmask_b32_e32 v111, v191, v111, vcc
	v_cmp_gt_u32_e32 vcc, s82, v150
	v_add_u32_e32 v150, 0xffffffa6, v16
	s_nop 0
	v_cndmask_b32_e32 v95, v191, v95, vcc
	v_cmp_gt_u32_e32 vcc, s82, v150
	v_add_u32_e32 v150, 0xffffff86, v16
	s_nop 0
	v_cndmask_b32_e32 v112, v191, v112, vcc
	v_cmp_gt_u32_e32 vcc, s82, v150
	v_add_u32_e32 v150, 0xffffffa5, v16
	v_add_u32_e32 v16, 0xffffff85, v16
	v_cndmask_b32_e32 v96, v191, v96, vcc
	v_cmp_gt_u32_e32 vcc, s82, v150
	s_nop 1
	v_cndmask_b32_e32 v113, v191, v113, vcc
	v_cmp_gt_u32_e32 vcc, s82, v16
	s_nop 1
	v_cndmask_b32_e32 v97, v191, v97, vcc
